# c8 plus L1 prefetch of the differential-attention rope table rows at the first rope iteration of the combined-projection epilogue
# baseline (speedup 1.0000x reference)
; #define GAS __attribute__((address_space(1)))
;     __device__ __forceinline__ void operator()(const f32x4 (&acc)[2][2][4][2], const pg8::Unit& u, int wr, int wc, int fr, int fq, const LAS float* scr) const {
;     ...
;             const int c0 = u.pn * 256 + bj * 128 + wc * 32, col0 = c0 + 8 * fq;
;             int kind = 0, j0 = 0; bool ffw = false;
;             if (mode == 1) {
;                 if (c0 >= PC_KR && c0 < PC_KR + 64) { kind = 1; j0 = ((c0 - PC_KR) >> 1) + 4 * fq; }
;                 else if (c0 >= PC_DQ && c0 < PC_DV && (c0 & 63) == 0 && fq < 2) { kind = 2; j0 = 4 * fq; }
;                 ffw = (c0 == PC_FF) && (fq == 0);
;             } else if (mode == 2) {
;                 if (((c0 & ~63) % 192) == 128) { kind = 1; j0 = ((c0 & 32) ? 16 : 0) + 4 * fq; }
;             }
; #pragma unroll
;             for (int ai = 0; ai < 2; ++ai)
; #pragma unroll
;                 for (int m = 0; m < 4; ++m) {
;                     const int row = row0 + ai * 128 + m * 16;
;                     const float sc_ = scr[ai * 128 + wr * 64 + m * 16 + fr]; f32x4 v0 = acc[ai][bj][m][0] * sc_, v1 = acc[ai][bj][m][1] * sc_;
;                     if (kind == 1) { const f32x4 c = *(const GAS f32x4*)(cosM + (size_t)row * 32 + j0), s = *(const GAS f32x4*)(sinM + (size_t)row * 32 + j0);
;                         const f32x4 a = v0 * c - v1 * s, b = v0 * s + v1 * c; v0 = a; v1 = b; }
;                     else if (kind == 2) { const f32x4 c = *(const GAS f32x4*)(cosD + (size_t)row * 8 + j0), s = *(const GAS f32x4*)(sinD + (size_t)row * 8 + j0);
;                         const f32x4 a = v0 * c - v1 * s, b = v0 * s + v1 * c; v0 = a; v1 = b; }
.LBB0_304:
	s_or_b64 exec, exec, s[0:1]
	v_mov_b32_e32 v0, v240
	s_lshl_b32 s0, s11, 8
	s_add_i32 s0, s0, s66
	v_and_b32_e32 v151, 15, v0
	v_or_b32_e32 v150, s0, v151
	s_lshl_b32 s0, s2, 10
	s_and_b32 s0, s0, 0x400
	s_add_i32 s0, s70, s0
	v_lshl_add_u32 v160, v151, 2, s0
	v_bfe_u32 v152, v0, 4, 2
	ds_read_b32 v0, v160
	s_lshl_b32 s11, s10, 8
	v_cmp_gt_u32_e32 vcc, 2, v152
	s_and_b64 s[50:51], s[30:31], vcc
	s_add_i32 s0, s11, 0xfffff300
	s_cmpk_lt_u32 s0, 0x400
	v_lshlrev_b32_e32 v161, 2, v152
	s_cselect_b64 s[0:1], -1, 0
	s_and_b64 s[54:55], s[0:1], s[50:51]
	s_waitcnt lgkmcnt(0)
	v_pk_mul_f32 v[138:139], v[138:139], v[0:1] op_sel_hi:[1,0]
	v_pk_mul_f32 v[136:137], v[136:137], v[0:1] op_sel_hi:[1,0]
	v_pk_mul_f32 v[154:155], v[134:135], v[0:1] op_sel_hi:[1,0]
	v_pk_mul_f32 v[132:133], v[132:133], v[0:1] op_sel_hi:[1,0]
	v_ashrrev_i32_e32 v151, 31, v150
	v_lshlrev_b32_e32 v0, 2, v161
	s_and_saveexec_b64 s[0:1], s[54:55]
	s_cbranch_execz .LBB0_306
	v_lshlrev_b64 v[134:135], 5, v[150:151]
	v_lshl_add_u64 v[162:163], s[24:25], 0, v[134:135]
	v_lshl_add_u64 v[162:163], v[162:163], 0, v[0:1]
	v_lshl_add_u64 v[134:135], s[22:23], 0, v[134:135]
	global_load_dword v200, v[162:163], off offset:512
	global_load_dword v201, v[162:163], off offset:1024
	global_load_dword v202, v[162:163], off offset:1536
	v_add_co_u32_e32 v208, vcc, 0x1000, v162
	s_nop 1
	v_addc_co_u32_e32 v209, vcc, 0, v163, vcc
	global_load_dword v203, v[208:209], off
	global_load_dword v204, v[208:209], off offset:512
	global_load_dword v205, v[208:209], off offset:1024
	global_load_dword v206, v[208:209], off offset:1536
	global_load_dwordx4 v[162:165], v[162:163], off
	v_lshl_add_u64 v[134:135], v[134:135], 0, v[0:1]
	global_load_dword v210, v[134:135], off offset:512
	global_load_dword v211, v[134:135], off offset:1024
	global_load_dword v212, v[134:135], off offset:1536
	v_add_co_u32_e32 v218, vcc, 0x1000, v134
	s_nop 1
	v_addc_co_u32_e32 v219, vcc, 0, v135, vcc
	global_load_dword v213, v[218:219], off
	global_load_dword v214, v[218:219], off offset:512
	global_load_dword v215, v[218:219], off offset:1024
	global_load_dword v216, v[218:219], off offset:1536
	global_load_dwordx4 v[166:169], v[134:135], off
	s_waitcnt vmcnt(0)
	v_pk_mul_f32 v[134:135], v[154:155], v[164:165]
	v_pk_mul_f32 v[170:171], v[132:133], v[162:163]
	v_pk_mul_f32 v[164:165], v[138:139], v[164:165]
	v_pk_mul_f32 v[162:163], v[136:137], v[162:163]
	v_pk_fma_f32 v[138:139], v[138:139], v[168:169], v[134:135] neg_lo:[0,0,1] neg_hi:[0,0,1]
	v_pk_fma_f32 v[136:137], v[136:137], v[166:167], v[170:171] neg_lo:[0,0,1] neg_hi:[0,0,1]
	v_pk_fma_f32 v[154:155], v[154:155], v[168:169], v[164:165]
	v_pk_fma_f32 v[132:133], v[132:133], v[166:167], v[162:163]
